# SwiGLU epilogue: output dwords lane-permuted (ds_bpermute) so four consecutive lanes store 64 contiguous bytes of one row, on top of v32
# speedup vs baseline: 1.0100x; 1.0100x over previous
; __device__ __forceinline__ unsigned cvt_pk_bf16(float lo, float hi) { unsigned r; asm volatile("v_cvt_pk_bf16_f32 %0, %1, %2" : "=v"(r) : "v"(lo), "v"(hi)); return r; }
; __device__ __forceinline__ float ld_agent(const rss_t* p) { return (float)__hip_atomic_load(p, __ATOMIC_RELAXED, __HIP_MEMORY_SCOPE_AGENT) * (1.0f / 16777216.0f); }
; __device__ __forceinline__ rss_t rss_fix(float ss) { return (rss_t)(ss * 16777216.0f); }
; __device__ __forceinline__ float rstd_of(const rss_t* rowss, int row) { return __builtin_amdgcn_rsqf(ld_agent(rowss + row) * (1.0f / 1024.0f) + 1e-6f); }
; __device__ __forceinline__ unsigned silu_pk(f32x2 g, f32x2 u, float k1, float k2) {
;     const f32x2 t = g * k1; f32x2 ex; ex.x = __builtin_amdgcn_exp2f(t.x); ex.y = __builtin_amdgcn_exp2f(t.y);
;     const f32x2 d = ex + 1.0f; f32x2 r; r.x = __builtin_amdgcn_rcpf(d.x); r.y = __builtin_amdgcn_rcpf(d.y);
;     const f32x2 o = (g * u) * (r * k2);
;     return cvt_pk_bf16(o.x, o.y);
;     __device__ __forceinline__ void operator()(const f32x4 (&acc)[2][2][4][2], const Unit& u, int wr, int wc, int fr, int fq) const {
;         const int row0 = u.pm * BM + wr * 64 + fr, col0 = u.pn * HALF + wc * 32 + 8 * fq;
;         float ssq[2][4];
; #pragma unroll
;         for (int ai = 0; ai < 2; ++ai)
; #pragma unroll
;             for (int m = 0; m < 4; ++m) ssq[ai][m] = ld_agent(rowss + row0 + ai * HALF + m * 16);
; #pragma unroll
;         for (int ai = 0; ai < 2; ++ai)
; #pragma unroll
;             for (int m = 0; m < 4; ++m) {
;                 const int row = row0 + ai * HALF + m * 16; const float rs = __builtin_amdgcn_rsqf(ssq[ai][m] * (1.0f / 1024.0f) + 1e-6f);
;                 const float k1 = -1.4426950408889634f * rs, k2 = rs * rs;
;                 u32x4 w;
; #pragma unroll
;                 for (int n = 0; n < 2; ++n) {
;                     const f32x4 gv = acc[ai][0][m][n], uv = acc[ai][1][m][n];
;                     const unsigned lo = silu_pk((f32x2){gv[0], gv[1]}, (f32x2){uv[0], uv[1]}, k1, k2), hi = silu_pk((f32x2){gv[2], gv[3]}, (f32x2){uv[2], uv[3]}, k1, k2);
;                     if (n == 0) { w.x = lo; w.y = hi; } else { w.z = lo; w.w = hi; }
;                 }
;                 *(u32x4*)(O + (size_t)row * ldc + col0) = w;
.LBB0_235:
	v_lshl_add_u32 v144, s36, 8, v146
	v_ashrrev_i32_e32 v145, 31, v144
	v_lshl_add_u64 v[154:155], v[144:145], 3, s[8:9]
	global_load_dwordx2 v[156:157], v[154:155], off sc1
	global_load_dwordx2 v[158:159], v[154:155], off offset:128 sc1
	global_load_dwordx2 v[160:161], v[154:155], off offset:256 sc1
	global_load_dwordx2 v[162:163], v[154:155], off offset:384 sc1
	global_load_dwordx2 v[164:165], v[154:155], off offset:1024 sc1
	global_load_dwordx2 v[166:167], v[154:155], off offset:1152 sc1
	global_load_dwordx2 v[168:169], v[154:155], off offset:1280 sc1
	global_load_dwordx2 v[170:171], v[154:155], off offset:1408 sc1
	v_pk_mul_f32 v[124:125], v[120:121], v[124:125]
	v_pk_mul_f32 v[126:127], v[122:123], v[126:127]
	v_pk_mul_f32 v[112:113], v[116:117], v[112:113]
	v_pk_mul_f32 v[114:115], v[118:119], v[114:115]
	v_pk_mul_f32 v[104:105], v[108:109], v[104:105]
	v_pk_mul_f32 v[106:107], v[110:111], v[106:107]
	v_pk_mul_f32 v[96:97], v[100:101], v[96:97]
	v_pk_mul_f32 v[98:99], v[102:103], v[98:99]
	v_pk_mul_f32 v[88:89], v[92:93], v[88:89]
	v_pk_mul_f32 v[90:91], v[94:95], v[90:91]
	v_pk_mul_f32 v[80:81], v[84:85], v[80:81]
	v_pk_mul_f32 v[82:83], v[86:87], v[82:83]
	v_pk_mul_f32 v[72:73], v[76:77], v[72:73]
	v_pk_mul_f32 v[74:75], v[78:79], v[74:75]
	v_pk_mul_f32 v[64:65], v[68:69], v[64:65]
	v_pk_mul_f32 v[66:67], v[70:71], v[66:67]
	v_pk_mul_f32 v[56:57], v[60:61], v[56:57]
	v_pk_mul_f32 v[58:59], v[62:63], v[58:59]
	v_pk_mul_f32 v[48:49], v[52:53], v[48:49]
	v_pk_mul_f32 v[50:51], v[54:55], v[50:51]
	v_pk_mul_f32 v[40:41], v[44:45], v[40:41]
	v_pk_mul_f32 v[42:43], v[46:47], v[42:43]
	v_pk_mul_f32 v[32:33], v[36:37], v[32:33]
	v_pk_mul_f32 v[34:35], v[38:39], v[34:35]
	v_pk_mul_f32 v[24:25], v[28:29], v[24:25]
	v_pk_mul_f32 v[26:27], v[30:31], v[26:27]
	v_pk_mul_f32 v[16:17], v[20:21], v[16:17]
	v_pk_mul_f32 v[18:19], v[22:23], v[18:19]
	v_pk_mul_f32 v[8:9], v[12:13], v[8:9]
	v_pk_mul_f32 v[10:11], v[14:15], v[10:11]
	v_pk_mul_f32 v[0:1], v[4:5], v[0:1]
	v_pk_mul_f32 v[2:3], v[6:7], v[2:3]
	v_and_b32_e32 v153, 63, v242
	v_and_b32_e32 v222, 3, v153
	v_lshrrev_b32_e32 v223, 2, v153
	v_lshlrev_b32_e32 v153, 6, v222
	v_lshl_or_b32 v153, v223, 2, v153
	v_and_b32_e32 v144, 64, v146
	v_or_b32_e32 v144, v144, v223
	v_lshl_add_u32 v144, s36, 8, v144
	v_and_b32_e32 v225, 0x60, v148
	v_lshl_or_b32 v222, v222, 3, v225
	v_lshl_or_b32 v222, s63, 7, v222
	v_mov_b32_e32 v223, 0
	v_mov_b64_e32 v[224:225], s[12:13]
	v_lshlrev_b64 v[222:223], 1, v[222:223]
	v_mad_i64_i32 v[220:221], s[38:39], v144, s59, v[224:225]
	s_mov_b64 s[96:97], 0x16000
	s_mov_b64 s[98:99], 0x6e000
	v_lshl_add_u64 v[220:221], v[220:221], 0, v[222:223]
	s_waitcnt vmcnt(0)
	v_cvt_f32_u32_e32 v188, v157
	v_cvt_f32_u32_e32 v190, v159
	v_cvt_f32_u32_e32 v192, v161
	v_cvt_f32_u32_e32 v194, v163
	v_cvt_f32_u32_e32 v196, v165
	v_cvt_f32_u32_e32 v198, v167
	v_cvt_f32_u32_e32 v200, v169
	v_cvt_f32_u32_e32 v202, v171
	v_cvt_f32_u32_e32 v189, v156
	v_cvt_f32_u32_e32 v191, v158
	v_cvt_f32_u32_e32 v193, v160
	v_cvt_f32_u32_e32 v195, v162
	v_cvt_f32_u32_e32 v197, v164
	v_cvt_f32_u32_e32 v199, v166
	v_cvt_f32_u32_e32 v201, v168
	v_cvt_f32_u32_e32 v203, v170
	v_fmamk_f32 v188, v188, 0x4f800000, v189
	v_fmamk_f32 v190, v190, 0x4f800000, v191
	v_fmamk_f32 v192, v192, 0x4f800000, v193
	v_fmamk_f32 v194, v194, 0x4f800000, v195
	v_fmamk_f32 v196, v196, 0x4f800000, v197
	v_fmamk_f32 v198, v198, 0x4f800000, v199
	v_fmamk_f32 v200, v200, 0x4f800000, v201
	v_fmamk_f32 v202, v202, 0x4f800000, v203
	v_fmamk_f32 v173, v188, 0x2e800000, v152
	v_fmamk_f32 v175, v190, 0x2e800000, v152
	v_fmamk_f32 v177, v192, 0x2e800000, v152
	v_fmamk_f32 v179, v194, 0x2e800000, v152
	v_fmamk_f32 v181, v196, 0x2e800000, v152
	v_fmamk_f32 v183, v198, 0x2e800000, v152
	v_fmamk_f32 v185, v200, 0x2e800000, v152
	v_fmamk_f32 v187, v202, 0x2e800000, v152
	v_rsq_f32_e32 v172, v173
	v_rsq_f32_e32 v174, v175
	v_rsq_f32_e32 v176, v177
	v_rsq_f32_e32 v178, v179
	v_rsq_f32_e32 v180, v181
	v_rsq_f32_e32 v182, v183
	v_rsq_f32_e32 v184, v185
	v_rsq_f32_e32 v186, v187
	v_mul_f32_e32 v172, 0xbfb8aa3b, v172
	v_mul_f32_e32 v174, 0xbfb8aa3b, v174
	v_mul_f32_e32 v176, 0xbfb8aa3b, v176
	v_mul_f32_e32 v178, 0xbfb8aa3b, v178
	v_mul_f32_e32 v180, 0xbfb8aa3b, v180
	v_mul_f32_e32 v182, 0xbfb8aa3b, v182
	v_mul_f32_e32 v184, 0xbfb8aa3b, v184
	v_mul_f32_e32 v186, 0xbfb8aa3b, v186
	v_pk_mul_f32 v[188:189], v[120:121], v[172:173] op_sel_hi:[1,0]
	v_pk_mul_f32 v[190:191], v[122:123], v[172:173] op_sel_hi:[1,0]
	v_pk_mul_f32 v[192:193], v[116:117], v[172:173] op_sel_hi:[1,0]
	v_pk_mul_f32 v[194:195], v[118:119], v[172:173] op_sel_hi:[1,0]
	v_pk_mul_f32 v[196:197], v[108:109], v[174:175] op_sel_hi:[1,0]
	v_pk_mul_f32 v[198:199], v[110:111], v[174:175] op_sel_hi:[1,0]
	v_pk_mul_f32 v[200:201], v[100:101], v[174:175] op_sel_hi:[1,0]
	v_pk_mul_f32 v[202:203], v[102:103], v[174:175] op_sel_hi:[1,0]
	v_exp_f32_e32 v188, v188
	v_exp_f32_e32 v189, v189
	v_exp_f32_e32 v190, v190
	v_exp_f32_e32 v191, v191
	v_exp_f32_e32 v192, v192
	v_exp_f32_e32 v193, v193
	v_exp_f32_e32 v194, v194
	v_exp_f32_e32 v195, v195
	v_exp_f32_e32 v196, v196
	v_exp_f32_e32 v197, v197
	v_exp_f32_e32 v198, v198
	v_exp_f32_e32 v199, v199
	v_exp_f32_e32 v200, v200
	v_exp_f32_e32 v201, v201
	v_exp_f32_e32 v202, v202
	v_exp_f32_e32 v203, v203
	v_pk_fma_f32 v[188:189], v[188:189], v[172:173], v[172:173] op_sel:[0,1,1] op_sel_hi:[1,1,1]
	v_pk_fma_f32 v[190:191], v[190:191], v[172:173], v[172:173] op_sel:[0,1,1] op_sel_hi:[1,1,1]
	v_pk_fma_f32 v[192:193], v[192:193], v[172:173], v[172:173] op_sel:[0,1,1] op_sel_hi:[1,1,1]
	v_pk_fma_f32 v[194:195], v[194:195], v[172:173], v[172:173] op_sel:[0,1,1] op_sel_hi:[1,1,1]
; __device__ __forceinline__ unsigned cvt_pk_bf16(float lo, float hi) { unsigned r; asm volatile("v_cvt_pk_bf16_f32 %0, %1, %2" : "=v"(r) : "v"(lo), "v"(hi)); return r; }
; __device__ __forceinline__ unsigned silu_pk(f32x2 g, f32x2 u, float k1, float k2) {
;     const f32x2 t = g * k1; f32x2 ex; ex.x = __builtin_amdgcn_exp2f(t.x); ex.y = __builtin_amdgcn_exp2f(t.y);
;     const f32x2 d = ex + 1.0f; f32x2 r; r.x = __builtin_amdgcn_rcpf(d.x); r.y = __builtin_amdgcn_rcpf(d.y);
;     const f32x2 o = (g * u) * (r * k2);
;     return cvt_pk_bf16(o.x, o.y);
;     __device__ __forceinline__ void operator()(const f32x4 (&acc)[2][2][4][2], const Unit& u, int wr, int wc, int fr, int fq) const {
;     ...
;             for (int m = 0; m < 4; ++m) {
;                 const int row = row0 + ai * HALF + m * 16; const float rs = __builtin_amdgcn_rsqf(ssq[ai][m] * (1.0f / 1024.0f) + 1e-6f);
;                 const float k1 = -1.4426950408889634f * rs, k2 = rs * rs;
;                 u32x4 w;
; #pragma unroll
;                 for (int n = 0; n < 2; ++n) {
;                     const f32x4 gv = acc[ai][0][m][n], uv = acc[ai][1][m][n];
;                     const unsigned lo = silu_pk((f32x2){gv[0], gv[1]}, (f32x2){uv[0], uv[1]}, k1, k2), hi = silu_pk((f32x2){gv[2], gv[3]}, (f32x2){uv[2], uv[3]}, k1, k2);
;                     if (n == 0) { w.x = lo; w.y = hi; } else { w.z = lo; w.w = hi; }
;                 }
;                 *(u32x4*)(O + (size_t)row * ldc + col0) = w;
	v_pk_fma_f32 v[196:197], v[196:197], v[174:175], v[174:175] op_sel:[0,1,1] op_sel_hi:[1,1,1]
	v_pk_fma_f32 v[198:199], v[198:199], v[174:175], v[174:175] op_sel:[0,1,1] op_sel_hi:[1,1,1]
	v_pk_fma_f32 v[200:201], v[200:201], v[174:175], v[174:175] op_sel:[0,1,1] op_sel_hi:[1,1,1]
	v_pk_fma_f32 v[202:203], v[202:203], v[174:175], v[174:175] op_sel:[0,1,1] op_sel_hi:[1,1,1]
	v_rcp_f32_e32 v188, v188
	v_rcp_f32_e32 v189, v189
	v_rcp_f32_e32 v190, v190
	v_rcp_f32_e32 v191, v191
	v_rcp_f32_e32 v192, v192
	v_rcp_f32_e32 v193, v193
	v_rcp_f32_e32 v194, v194
	v_rcp_f32_e32 v195, v195
	v_rcp_f32_e32 v196, v196
	v_rcp_f32_e32 v197, v197
	v_rcp_f32_e32 v198, v198
	v_rcp_f32_e32 v199, v199
	v_rcp_f32_e32 v200, v200
	v_rcp_f32_e32 v201, v201
	v_rcp_f32_e32 v202, v202
	v_rcp_f32_e32 v203, v203
	v_pk_mul_f32 v[188:189], v[124:125], v[188:189]
	v_pk_mul_f32 v[190:191], v[126:127], v[190:191]
	v_pk_mul_f32 v[192:193], v[112:113], v[192:193]
	v_pk_mul_f32 v[194:195], v[114:115], v[194:195]
	v_pk_mul_f32 v[196:197], v[104:105], v[196:197]
	v_pk_mul_f32 v[198:199], v[106:107], v[198:199]
	v_pk_mul_f32 v[200:201], v[96:97], v[200:201]
	v_pk_mul_f32 v[202:203], v[98:99], v[202:203]
	v_cvt_pk_bf16_f32 v204, v188, v189
	v_cvt_pk_bf16_f32 v205, v190, v191
	v_cvt_pk_bf16_f32 v206, v192, v193
	v_cvt_pk_bf16_f32 v207, v194, v195
	v_cvt_pk_bf16_f32 v208, v196, v197
	v_cvt_pk_bf16_f32 v209, v198, v199
	v_cvt_pk_bf16_f32 v210, v200, v201
	v_cvt_pk_bf16_f32 v211, v202, v203
	ds_bpermute_b32 v226, v153, v204
	ds_bpermute_b32 v227, v153, v205
	ds_bpermute_b32 v228, v153, v206
	ds_bpermute_b32 v229, v153, v207
	ds_bpermute_b32 v230, v153, v208
	ds_bpermute_b32 v231, v153, v209
	ds_bpermute_b32 v232, v153, v210
	ds_bpermute_b32 v233, v153, v211
	v_pk_mul_f32 v[188:189], v[92:93], v[176:177] op_sel_hi:[1,0]
	v_pk_mul_f32 v[190:191], v[94:95], v[176:177] op_sel_hi:[1,0]
	v_pk_mul_f32 v[192:193], v[84:85], v[176:177] op_sel_hi:[1,0]
	v_pk_mul_f32 v[194:195], v[86:87], v[176:177] op_sel_hi:[1,0]
	v_pk_mul_f32 v[196:197], v[76:77], v[178:179] op_sel_hi:[1,0]
	v_pk_mul_f32 v[198:199], v[78:79], v[178:179] op_sel_hi:[1,0]
	v_pk_mul_f32 v[200:201], v[68:69], v[178:179] op_sel_hi:[1,0]
	v_pk_mul_f32 v[202:203], v[70:71], v[178:179] op_sel_hi:[1,0]
	v_exp_f32_e32 v188, v188
	v_exp_f32_e32 v189, v189
	v_exp_f32_e32 v190, v190
	v_exp_f32_e32 v191, v191
	v_exp_f32_e32 v192, v192
	v_exp_f32_e32 v193, v193
	v_exp_f32_e32 v194, v194
	v_exp_f32_e32 v195, v195
	v_exp_f32_e32 v196, v196
	v_exp_f32_e32 v197, v197
	v_exp_f32_e32 v198, v198
	v_exp_f32_e32 v199, v199
	v_exp_f32_e32 v200, v200
	v_exp_f32_e32 v201, v201
	v_exp_f32_e32 v202, v202
	v_exp_f32_e32 v203, v203
	v_pk_fma_f32 v[188:189], v[188:189], v[176:177], v[176:177] op_sel:[0,1,1] op_sel_hi:[1,1,1]
	v_pk_fma_f32 v[190:191], v[190:191], v[176:177], v[176:177] op_sel:[0,1,1] op_sel_hi:[1,1,1]
	v_pk_fma_f32 v[192:193], v[192:193], v[176:177], v[176:177] op_sel:[0,1,1] op_sel_hi:[1,1,1]
	v_pk_fma_f32 v[194:195], v[194:195], v[176:177], v[176:177] op_sel:[0,1,1] op_sel_hi:[1,1,1]
	v_pk_fma_f32 v[196:197], v[196:197], v[178:179], v[178:179] op_sel:[0,1,1] op_sel_hi:[1,1,1]
	v_pk_fma_f32 v[198:199], v[198:199], v[178:179], v[178:179] op_sel:[0,1,1] op_sel_hi:[1,1,1]
	v_pk_fma_f32 v[200:201], v[200:201], v[178:179], v[178:179] op_sel:[0,1,1] op_sel_hi:[1,1,1]
	v_pk_fma_f32 v[202:203], v[202:203], v[178:179], v[178:179] op_sel:[0,1,1] op_sel_hi:[1,1,1]
	v_rcp_f32_e32 v188, v188
	v_rcp_f32_e32 v189, v189
	v_rcp_f32_e32 v190, v190
	v_rcp_f32_e32 v191, v191
	v_rcp_f32_e32 v192, v192
	v_rcp_f32_e32 v193, v193
	v_rcp_f32_e32 v194, v194
	v_rcp_f32_e32 v195, v195
	v_rcp_f32_e32 v196, v196
	v_rcp_f32_e32 v197, v197
	v_rcp_f32_e32 v198, v198
	v_rcp_f32_e32 v199, v199
	v_rcp_f32_e32 v200, v200
	v_rcp_f32_e32 v201, v201
	v_rcp_f32_e32 v202, v202
	v_rcp_f32_e32 v203, v203
	v_pk_mul_f32 v[188:189], v[88:89], v[188:189]
	v_pk_mul_f32 v[190:191], v[90:91], v[190:191]
	v_pk_mul_f32 v[192:193], v[80:81], v[192:193]
	v_pk_mul_f32 v[194:195], v[82:83], v[194:195]
	v_pk_mul_f32 v[196:197], v[72:73], v[196:197]
	v_pk_mul_f32 v[198:199], v[74:75], v[198:199]
	v_pk_mul_f32 v[200:201], v[64:65], v[200:201]
	v_pk_mul_f32 v[202:203], v[66:67], v[202:203]
	v_cvt_pk_bf16_f32 v212, v188, v189
	v_cvt_pk_bf16_f32 v213, v190, v191
	v_cvt_pk_bf16_f32 v214, v192, v193
	v_cvt_pk_bf16_f32 v215, v194, v195
	v_cvt_pk_bf16_f32 v216, v196, v197
	v_cvt_pk_bf16_f32 v217, v198, v199
	v_cvt_pk_bf16_f32 v218, v200, v201
	v_cvt_pk_bf16_f32 v219, v202, v203
	ds_bpermute_b32 v234, v153, v212
	ds_bpermute_b32 v235, v153, v213
	ds_bpermute_b32 v236, v153, v214
	ds_bpermute_b32 v237, v153, v215
	ds_bpermute_b32 v238, v153, v216
	ds_bpermute_b32 v239, v153, v217
	ds_bpermute_b32 v240, v153, v218
	ds_bpermute_b32 v241, v153, v219
	s_waitcnt lgkmcnt(8)
; __device__ __forceinline__ unsigned cvt_pk_bf16(float lo, float hi) { unsigned r; asm volatile("v_cvt_pk_bf16_f32 %0, %1, %2" : "=v"(r) : "v"(lo), "v"(hi)); return r; }
; __device__ __forceinline__ unsigned silu_pk(f32x2 g, f32x2 u, float k1, float k2) {
;     const f32x2 t = g * k1; f32x2 ex; ex.x = __builtin_amdgcn_exp2f(t.x); ex.y = __builtin_amdgcn_exp2f(t.y);
;     const f32x2 d = ex + 1.0f; f32x2 r; r.x = __builtin_amdgcn_rcpf(d.x); r.y = __builtin_amdgcn_rcpf(d.y);
;     const f32x2 o = (g * u) * (r * k2);
;     return cvt_pk_bf16(o.x, o.y);
;     __device__ __forceinline__ void operator()(const f32x4 (&acc)[2][2][4][2], const Unit& u, int wr, int wc, int fr, int fq) const {
;     ...
;             for (int m = 0; m < 4; ++m) {
;                 const int row = row0 + ai * HALF + m * 16; const float rs = __builtin_amdgcn_rsqf(ssq[ai][m] * (1.0f / 1024.0f) + 1e-6f);
;                 const float k1 = -1.4426950408889634f * rs, k2 = rs * rs;
;                 u32x4 w;
; #pragma unroll
;                 for (int n = 0; n < 2; ++n) {
;                     const f32x4 gv = acc[ai][0][m][n], uv = acc[ai][1][m][n];
;                     const unsigned lo = silu_pk((f32x2){gv[0], gv[1]}, (f32x2){uv[0], uv[1]}, k1, k2), hi = silu_pk((f32x2){gv[2], gv[3]}, (f32x2){uv[2], uv[3]}, k1, k2);
;                     if (n == 0) { w.x = lo; w.y = hi; } else { w.z = lo; w.w = hi; }
;                 }
;                 *(u32x4*)(O + (size_t)row * ldc + col0) = w;
	global_store_dwordx4 v[220:221], v[226:229], off
	v_lshl_add_u64 v[220:221], v[220:221], 0, s[96:97]
	global_store_dwordx4 v[220:221], v[230:233], off
	v_lshl_add_u64 v[220:221], v[220:221], 0, s[96:97]
	v_pk_mul_f32 v[188:189], v[60:61], v[180:181] op_sel_hi:[1,0]
	v_pk_mul_f32 v[190:191], v[62:63], v[180:181] op_sel_hi:[1,0]
	v_pk_mul_f32 v[192:193], v[52:53], v[180:181] op_sel_hi:[1,0]
	v_pk_mul_f32 v[194:195], v[54:55], v[180:181] op_sel_hi:[1,0]
	v_pk_mul_f32 v[196:197], v[44:45], v[182:183] op_sel_hi:[1,0]
	v_pk_mul_f32 v[198:199], v[46:47], v[182:183] op_sel_hi:[1,0]
	v_pk_mul_f32 v[200:201], v[36:37], v[182:183] op_sel_hi:[1,0]
	v_pk_mul_f32 v[202:203], v[38:39], v[182:183] op_sel_hi:[1,0]
	v_exp_f32_e32 v188, v188
	v_exp_f32_e32 v189, v189
	v_exp_f32_e32 v190, v190
	v_exp_f32_e32 v191, v191
	v_exp_f32_e32 v192, v192
	v_exp_f32_e32 v193, v193
	v_exp_f32_e32 v194, v194
	v_exp_f32_e32 v195, v195
	v_exp_f32_e32 v196, v196
	v_exp_f32_e32 v197, v197
	v_exp_f32_e32 v198, v198
	v_exp_f32_e32 v199, v199
	v_exp_f32_e32 v200, v200
	v_exp_f32_e32 v201, v201
	v_exp_f32_e32 v202, v202
	v_exp_f32_e32 v203, v203
	v_pk_fma_f32 v[188:189], v[188:189], v[180:181], v[180:181] op_sel:[0,1,1] op_sel_hi:[1,1,1]
	v_pk_fma_f32 v[190:191], v[190:191], v[180:181], v[180:181] op_sel:[0,1,1] op_sel_hi:[1,1,1]
	v_pk_fma_f32 v[192:193], v[192:193], v[180:181], v[180:181] op_sel:[0,1,1] op_sel_hi:[1,1,1]
	v_pk_fma_f32 v[194:195], v[194:195], v[180:181], v[180:181] op_sel:[0,1,1] op_sel_hi:[1,1,1]
	v_pk_fma_f32 v[196:197], v[196:197], v[182:183], v[182:183] op_sel:[0,1,1] op_sel_hi:[1,1,1]
	v_pk_fma_f32 v[198:199], v[198:199], v[182:183], v[182:183] op_sel:[0,1,1] op_sel_hi:[1,1,1]
	v_pk_fma_f32 v[200:201], v[200:201], v[182:183], v[182:183] op_sel:[0,1,1] op_sel_hi:[1,1,1]
	v_pk_fma_f32 v[202:203], v[202:203], v[182:183], v[182:183] op_sel:[0,1,1] op_sel_hi:[1,1,1]
	v_rcp_f32_e32 v188, v188
	v_rcp_f32_e32 v189, v189
	v_rcp_f32_e32 v190, v190
	v_rcp_f32_e32 v191, v191
	v_rcp_f32_e32 v192, v192
	v_rcp_f32_e32 v193, v193
	v_rcp_f32_e32 v194, v194
	v_rcp_f32_e32 v195, v195
	v_rcp_f32_e32 v196, v196
	v_rcp_f32_e32 v197, v197
	v_rcp_f32_e32 v198, v198
	v_rcp_f32_e32 v199, v199
	v_rcp_f32_e32 v200, v200
	v_rcp_f32_e32 v201, v201
	v_rcp_f32_e32 v202, v202
	v_rcp_f32_e32 v203, v203
	v_pk_mul_f32 v[188:189], v[56:57], v[188:189]
	v_pk_mul_f32 v[190:191], v[58:59], v[190:191]
	v_pk_mul_f32 v[192:193], v[48:49], v[192:193]
	v_pk_mul_f32 v[194:195], v[50:51], v[194:195]
	v_pk_mul_f32 v[196:197], v[40:41], v[196:197]
	v_pk_mul_f32 v[198:199], v[42:43], v[198:199]
	v_pk_mul_f32 v[200:201], v[32:33], v[200:201]
	v_pk_mul_f32 v[202:203], v[34:35], v[202:203]
	v_cvt_pk_bf16_f32 v204, v188, v189
	v_cvt_pk_bf16_f32 v205, v190, v191
	v_cvt_pk_bf16_f32 v206, v192, v193
	v_cvt_pk_bf16_f32 v207, v194, v195
	v_cvt_pk_bf16_f32 v208, v196, v197
	v_cvt_pk_bf16_f32 v209, v198, v199
	v_cvt_pk_bf16_f32 v210, v200, v201
	v_cvt_pk_bf16_f32 v211, v202, v203
	ds_bpermute_b32 v226, v153, v204
	ds_bpermute_b32 v227, v153, v205
	ds_bpermute_b32 v228, v153, v206
	ds_bpermute_b32 v229, v153, v207
	ds_bpermute_b32 v230, v153, v208
	ds_bpermute_b32 v231, v153, v209
	ds_bpermute_b32 v232, v153, v210
	ds_bpermute_b32 v233, v153, v211
	s_waitcnt lgkmcnt(8)
	global_store_dwordx4 v[220:221], v[234:237], off
	v_lshl_add_u64 v[220:221], v[220:221], 0, s[96:97]
	global_store_dwordx4 v[220:221], v[238:241], off
	v_lshl_add_u64 v[220:221], v[220:221], 0, s[98:99]
	v_pk_mul_f32 v[188:189], v[28:29], v[184:185] op_sel_hi:[1,0]
	v_pk_mul_f32 v[190:191], v[30:31], v[184:185] op_sel_hi:[1,0]
	v_pk_mul_f32 v[192:193], v[20:21], v[184:185] op_sel_hi:[1,0]
	v_pk_mul_f32 v[194:195], v[22:23], v[184:185] op_sel_hi:[1,0]
	v_pk_mul_f32 v[196:197], v[12:13], v[186:187] op_sel_hi:[1,0]
	v_pk_mul_f32 v[198:199], v[14:15], v[186:187] op_sel_hi:[1,0]
	v_pk_mul_f32 v[200:201], v[4:5], v[186:187] op_sel_hi:[1,0]
	v_pk_mul_f32 v[202:203], v[6:7], v[186:187] op_sel_hi:[1,0]
	v_exp_f32_e32 v188, v188
	v_exp_f32_e32 v189, v189
	v_exp_f32_e32 v190, v190
	v_exp_f32_e32 v191, v191
	v_exp_f32_e32 v192, v192
	v_exp_f32_e32 v193, v193
	v_exp_f32_e32 v194, v194
	v_exp_f32_e32 v195, v195
	v_exp_f32_e32 v196, v196
	v_exp_f32_e32 v197, v197
	v_exp_f32_e32 v198, v198
	v_exp_f32_e32 v199, v199
	v_exp_f32_e32 v200, v200
	v_exp_f32_e32 v201, v201
	v_exp_f32_e32 v202, v202
	v_exp_f32_e32 v203, v203
	v_pk_fma_f32 v[188:189], v[188:189], v[184:185], v[184:185] op_sel:[0,1,1] op_sel_hi:[1,1,1]
	v_pk_fma_f32 v[190:191], v[190:191], v[184:185], v[184:185] op_sel:[0,1,1] op_sel_hi:[1,1,1]
	v_pk_fma_f32 v[192:193], v[192:193], v[184:185], v[184:185] op_sel:[0,1,1] op_sel_hi:[1,1,1]
	v_pk_fma_f32 v[194:195], v[194:195], v[184:185], v[184:185] op_sel:[0,1,1] op_sel_hi:[1,1,1]
	v_pk_fma_f32 v[196:197], v[196:197], v[186:187], v[186:187] op_sel:[0,1,1] op_sel_hi:[1,1,1]
	v_pk_fma_f32 v[198:199], v[198:199], v[186:187], v[186:187] op_sel:[0,1,1] op_sel_hi:[1,1,1]
	v_pk_fma_f32 v[200:201], v[200:201], v[186:187], v[186:187] op_sel:[0,1,1] op_sel_hi:[1,1,1]
	v_pk_fma_f32 v[202:203], v[202:203], v[186:187], v[186:187] op_sel:[0,1,1] op_sel_hi:[1,1,1]
	v_rcp_f32_e32 v188, v188
	v_rcp_f32_e32 v189, v189
	v_rcp_f32_e32 v190, v190
	v_rcp_f32_e32 v191, v191
	v_rcp_f32_e32 v192, v192
	v_rcp_f32_e32 v193, v193
	v_rcp_f32_e32 v194, v194
	v_rcp_f32_e32 v195, v195
	v_rcp_f32_e32 v196, v196
	v_rcp_f32_e32 v197, v197
	v_rcp_f32_e32 v198, v198
	v_rcp_f32_e32 v199, v199
	v_rcp_f32_e32 v200, v200
	v_rcp_f32_e32 v201, v201
	v_rcp_f32_e32 v202, v202
	v_rcp_f32_e32 v203, v203
	v_pk_mul_f32 v[188:189], v[24:25], v[188:189]
	v_pk_mul_f32 v[190:191], v[26:27], v[190:191]
	v_pk_mul_f32 v[192:193], v[16:17], v[192:193]
	v_pk_mul_f32 v[194:195], v[18:19], v[194:195]
	v_pk_mul_f32 v[196:197], v[8:9], v[196:197]
	v_pk_mul_f32 v[198:199], v[10:11], v[198:199]
	v_pk_mul_f32 v[200:201], v[0:1], v[200:201]
	v_pk_mul_f32 v[202:203], v[2:3], v[202:203]
	v_cvt_pk_bf16_f32 v212, v188, v189
	v_cvt_pk_bf16_f32 v213, v190, v191
	v_cvt_pk_bf16_f32 v214, v192, v193
	v_cvt_pk_bf16_f32 v215, v194, v195
	v_cvt_pk_bf16_f32 v216, v196, v197
	v_cvt_pk_bf16_f32 v217, v198, v199
	v_cvt_pk_bf16_f32 v218, v200, v201
	v_cvt_pk_bf16_f32 v219, v202, v203
	ds_bpermute_b32 v234, v153, v212
	ds_bpermute_b32 v235, v153, v213
	ds_bpermute_b32 v236, v153, v214
	ds_bpermute_b32 v237, v153, v215
	ds_bpermute_b32 v238, v153, v216
	ds_bpermute_b32 v239, v153, v217
	ds_bpermute_b32 v240, v153, v218
	ds_bpermute_b32 v241, v153, v219
	s_waitcnt lgkmcnt(8)
	global_store_dwordx4 v[220:221], v[226:229], off
	v_lshl_add_u64 v[220:221], v[220:221], 0, s[96:97]
	global_store_dwordx4 v[220:221], v[230:233], off
	v_lshl_add_u64 v[220:221], v[220:221], 0, s[96:97]
	s_waitcnt lgkmcnt(0)
	global_store_dwordx4 v[220:221], v[234:237], off
	v_lshl_add_u64 v[220:221], v[220:221], 0, s[96:97]
	global_store_dwordx4 v[220:221], v[238:241], off
	s_andn2_b64 vcc, exec, s[4:5]
	s_mov_b64 s[4:5], -1
	s_cbranch_vccnz .LBB0_228
	s_andn2_b64 vcc, exec, s[6:7]
	s_cbranch_vccnz .LBB0_227
	s_barrier
	s_branch .LBB0_227

; __device__ __forceinline__ unsigned cvt_pk_bf16(float lo, float hi) { unsigned r; asm volatile("v_cvt_pk_bf16_f32 %0, %1, %2" : "=v"(r) : "v"(lo), "v"(hi)); return r; }
; __device__ __forceinline__ float ld_agent(const rss_t* p) { return (float)__hip_atomic_load(p, __ATOMIC_RELAXED, __HIP_MEMORY_SCOPE_AGENT) * (1.0f / 16777216.0f); }
; __device__ __forceinline__ unsigned silu_pk(f32x2 g, f32x2 u, float k1, float k2) {
;     const f32x2 t = g * k1; f32x2 ex; ex.x = __builtin_amdgcn_exp2f(t.x); ex.y = __builtin_amdgcn_exp2f(t.y);
;     const f32x2 d = ex + 1.0f; f32x2 r; r.x = __builtin_amdgcn_rcpf(d.x); r.y = __builtin_amdgcn_rcpf(d.y);
;     const f32x2 o = (g * u) * (r * k2);
;     return cvt_pk_bf16(o.x, o.y);
;     __device__ __forceinline__ void operator()(const f32x4 (&acc)[2][2][4][2], const Unit& u, int wr, int wc, int fr, int fq) const {
;         const int row0 = u.pm * BM + wr * 64 + fr, col0 = u.pn * HALF + wc * 32 + 8 * fq;
;         float ssq[2][4];
; #pragma unroll
;         for (int ai = 0; ai < 2; ++ai)
; #pragma unroll
;             for (int m = 0; m < 4; ++m) ssq[ai][m] = ld_agent(rowss + row0 + ai * HALF + m * 16);
; #pragma unroll
;         for (int ai = 0; ai < 2; ++ai)
; #pragma unroll
;             for (int m = 0; m < 4; ++m) {
;                 const int row = row0 + ai * HALF + m * 16; const float rs = __builtin_amdgcn_rsqf(ssq[ai][m] * (1.0f / 1024.0f) + 1e-6f);
;                 const float k1 = -1.4426950408889634f * rs, k2 = rs * rs;
;                 u32x4 w;
; #pragma unroll
;                 for (int n = 0; n < 2; ++n) {
;                     const f32x4 gv = acc[ai][0][m][n], uv = acc[ai][1][m][n];
;                     const unsigned lo = silu_pk((f32x2){gv[0], gv[1]}, (f32x2){uv[0], uv[1]}, k1, k2), hi = silu_pk((f32x2){gv[2], gv[3]}, (f32x2){uv[2], uv[3]}, k1, k2);
;                     if (n == 0) { w.x = lo; w.y = hi; } else { w.z = lo; w.w = hi; }
;                 }
;                 *(u32x4*)(O + (size_t)row * ldc + col0) = w;
.LBB0_1197:
	v_lshl_add_u32 v144, s36, 8, v146
	v_ashrrev_i32_e32 v145, 31, v144
	v_lshl_add_u64 v[154:155], v[144:145], 3, s[12:13]
	global_load_dwordx2 v[156:157], v[154:155], off sc1
	global_load_dwordx2 v[158:159], v[154:155], off offset:128 sc1
	global_load_dwordx2 v[160:161], v[154:155], off offset:256 sc1
	global_load_dwordx2 v[162:163], v[154:155], off offset:384 sc1
	global_load_dwordx2 v[164:165], v[154:155], off offset:1024 sc1
	global_load_dwordx2 v[166:167], v[154:155], off offset:1152 sc1
	global_load_dwordx2 v[168:169], v[154:155], off offset:1280 sc1
	global_load_dwordx2 v[170:171], v[154:155], off offset:1408 sc1
	v_pk_mul_f32 v[124:125], v[120:121], v[124:125]
	v_pk_mul_f32 v[126:127], v[122:123], v[126:127]
	v_pk_mul_f32 v[112:113], v[116:117], v[112:113]
	v_pk_mul_f32 v[114:115], v[118:119], v[114:115]
	v_pk_mul_f32 v[104:105], v[108:109], v[104:105]
	v_pk_mul_f32 v[106:107], v[110:111], v[106:107]
	v_pk_mul_f32 v[96:97], v[100:101], v[96:97]
	v_pk_mul_f32 v[98:99], v[102:103], v[98:99]
	v_pk_mul_f32 v[88:89], v[92:93], v[88:89]
	v_pk_mul_f32 v[90:91], v[94:95], v[90:91]
	v_pk_mul_f32 v[80:81], v[84:85], v[80:81]
	v_pk_mul_f32 v[82:83], v[86:87], v[82:83]
	v_pk_mul_f32 v[72:73], v[76:77], v[72:73]
	v_pk_mul_f32 v[74:75], v[78:79], v[74:75]
	v_pk_mul_f32 v[64:65], v[68:69], v[64:65]
	v_pk_mul_f32 v[66:67], v[70:71], v[66:67]
	v_pk_mul_f32 v[56:57], v[60:61], v[56:57]
	v_pk_mul_f32 v[58:59], v[62:63], v[58:59]
	v_pk_mul_f32 v[48:49], v[52:53], v[48:49]
	v_pk_mul_f32 v[50:51], v[54:55], v[50:51]
	v_pk_mul_f32 v[40:41], v[44:45], v[40:41]
	v_pk_mul_f32 v[42:43], v[46:47], v[42:43]
	v_pk_mul_f32 v[32:33], v[36:37], v[32:33]
	v_pk_mul_f32 v[34:35], v[38:39], v[34:35]
	v_pk_mul_f32 v[24:25], v[28:29], v[24:25]
	v_pk_mul_f32 v[26:27], v[30:31], v[26:27]
	v_pk_mul_f32 v[16:17], v[20:21], v[16:17]
	v_pk_mul_f32 v[18:19], v[22:23], v[18:19]
	v_pk_mul_f32 v[8:9], v[12:13], v[8:9]
	v_pk_mul_f32 v[10:11], v[14:15], v[10:11]
	v_pk_mul_f32 v[0:1], v[4:5], v[0:1]
	v_pk_mul_f32 v[2:3], v[6:7], v[2:3]
	v_and_b32_e32 v153, 63, v242
	v_and_b32_e32 v222, 3, v153
	v_lshrrev_b32_e32 v223, 2, v153
	v_lshlrev_b32_e32 v153, 6, v222
	v_lshl_or_b32 v153, v223, 2, v153
	v_and_b32_e32 v144, 64, v146
	v_or_b32_e32 v144, v144, v223
	v_lshl_add_u32 v144, s36, 8, v144
	v_and_b32_e32 v225, 0x60, v148
	v_lshl_or_b32 v222, v222, 3, v225
	v_lshl_or_b32 v222, s63, 7, v222
	v_mov_b32_e32 v223, 0
	v_mov_b64_e32 v[224:225], s[8:9]
	v_lshlrev_b64 v[222:223], 1, v[222:223]
	v_mad_i64_i32 v[220:221], s[38:39], v144, s59, v[224:225]
	s_mov_b64 s[96:97], 0x16000
	s_mov_b64 s[98:99], 0x6e000
	v_lshl_add_u64 v[220:221], v[220:221], 0, v[222:223]
	s_waitcnt vmcnt(0)
	v_cvt_f32_u32_e32 v188, v157
	v_cvt_f32_u32_e32 v190, v159
	v_cvt_f32_u32_e32 v192, v161
	v_cvt_f32_u32_e32 v194, v163
	v_cvt_f32_u32_e32 v196, v165
	v_cvt_f32_u32_e32 v198, v167
	v_cvt_f32_u32_e32 v200, v169
	v_cvt_f32_u32_e32 v202, v171
	v_cvt_f32_u32_e32 v189, v156
	v_cvt_f32_u32_e32 v191, v158
	v_cvt_f32_u32_e32 v193, v160
	v_cvt_f32_u32_e32 v195, v162
	v_cvt_f32_u32_e32 v197, v164
	v_cvt_f32_u32_e32 v199, v166
	v_cvt_f32_u32_e32 v201, v168
	v_cvt_f32_u32_e32 v203, v170
	v_fmamk_f32 v188, v188, 0x4f800000, v189
	v_fmamk_f32 v190, v190, 0x4f800000, v191
	v_fmamk_f32 v192, v192, 0x4f800000, v193
	v_fmamk_f32 v194, v194, 0x4f800000, v195
	v_fmamk_f32 v196, v196, 0x4f800000, v197
	v_fmamk_f32 v198, v198, 0x4f800000, v199
	v_fmamk_f32 v200, v200, 0x4f800000, v201
	v_fmamk_f32 v202, v202, 0x4f800000, v203
	v_fmamk_f32 v173, v188, 0x2e800000, v152
	v_fmamk_f32 v175, v190, 0x2e800000, v152
	v_fmamk_f32 v177, v192, 0x2e800000, v152
	v_fmamk_f32 v179, v194, 0x2e800000, v152
	v_fmamk_f32 v181, v196, 0x2e800000, v152
	v_fmamk_f32 v183, v198, 0x2e800000, v152
	v_fmamk_f32 v185, v200, 0x2e800000, v152
	v_fmamk_f32 v187, v202, 0x2e800000, v152
	v_rsq_f32_e32 v172, v173
	v_rsq_f32_e32 v174, v175
	v_rsq_f32_e32 v176, v177
	v_rsq_f32_e32 v178, v179
	v_rsq_f32_e32 v180, v181
	v_rsq_f32_e32 v182, v183
	v_rsq_f32_e32 v184, v185
	v_rsq_f32_e32 v186, v187
	v_mul_f32_e32 v172, 0xbfb8aa3b, v172
	v_mul_f32_e32 v174, 0xbfb8aa3b, v174
	v_mul_f32_e32 v176, 0xbfb8aa3b, v176
	v_mul_f32_e32 v178, 0xbfb8aa3b, v178
	v_mul_f32_e32 v180, 0xbfb8aa3b, v180
	v_mul_f32_e32 v182, 0xbfb8aa3b, v182
	v_mul_f32_e32 v184, 0xbfb8aa3b, v184
	v_mul_f32_e32 v186, 0xbfb8aa3b, v186
	v_pk_mul_f32 v[188:189], v[120:121], v[172:173] op_sel_hi:[1,0]
	v_pk_mul_f32 v[190:191], v[122:123], v[172:173] op_sel_hi:[1,0]
	v_pk_mul_f32 v[192:193], v[116:117], v[172:173] op_sel_hi:[1,0]
	v_pk_mul_f32 v[194:195], v[118:119], v[172:173] op_sel_hi:[1,0]
	v_pk_mul_f32 v[196:197], v[108:109], v[174:175] op_sel_hi:[1,0]
	v_pk_mul_f32 v[198:199], v[110:111], v[174:175] op_sel_hi:[1,0]
	v_pk_mul_f32 v[200:201], v[100:101], v[174:175] op_sel_hi:[1,0]
	v_pk_mul_f32 v[202:203], v[102:103], v[174:175] op_sel_hi:[1,0]
	v_exp_f32_e32 v188, v188
	v_exp_f32_e32 v189, v189
	v_exp_f32_e32 v190, v190
	v_exp_f32_e32 v191, v191
	v_exp_f32_e32 v192, v192
	v_exp_f32_e32 v193, v193
	v_exp_f32_e32 v194, v194
	v_exp_f32_e32 v195, v195
	v_exp_f32_e32 v196, v196
	v_exp_f32_e32 v197, v197
	v_exp_f32_e32 v198, v198
	v_exp_f32_e32 v199, v199
	v_exp_f32_e32 v200, v200
	v_exp_f32_e32 v201, v201
	v_exp_f32_e32 v202, v202
	v_exp_f32_e32 v203, v203
	v_pk_fma_f32 v[188:189], v[188:189], v[172:173], v[172:173] op_sel:[0,1,1] op_sel_hi:[1,1,1]
	v_pk_fma_f32 v[190:191], v[190:191], v[172:173], v[172:173] op_sel:[0,1,1] op_sel_hi:[1,1,1]
	v_pk_fma_f32 v[192:193], v[192:193], v[172:173], v[172:173] op_sel:[0,1,1] op_sel_hi:[1,1,1]
	v_pk_fma_f32 v[194:195], v[194:195], v[172:173], v[172:173] op_sel:[0,1,1] op_sel_hi:[1,1,1]
; __device__ __forceinline__ unsigned cvt_pk_bf16(float lo, float hi) { unsigned r; asm volatile("v_cvt_pk_bf16_f32 %0, %1, %2" : "=v"(r) : "v"(lo), "v"(hi)); return r; }
; __device__ __forceinline__ unsigned silu_pk(f32x2 g, f32x2 u, float k1, float k2) {
;     const f32x2 t = g * k1; f32x2 ex; ex.x = __builtin_amdgcn_exp2f(t.x); ex.y = __builtin_amdgcn_exp2f(t.y);
;     const f32x2 d = ex + 1.0f; f32x2 r; r.x = __builtin_amdgcn_rcpf(d.x); r.y = __builtin_amdgcn_rcpf(d.y);
;     const f32x2 o = (g * u) * (r * k2);
;     return cvt_pk_bf16(o.x, o.y);
;     __device__ __forceinline__ void operator()(const f32x4 (&acc)[2][2][4][2], const Unit& u, int wr, int wc, int fr, int fq) const {
;     ...
;             for (int m = 0; m < 4; ++m) {
;                 const int row = row0 + ai * HALF + m * 16; const float rs = __builtin_amdgcn_rsqf(ssq[ai][m] * (1.0f / 1024.0f) + 1e-6f);
;                 const float k1 = -1.4426950408889634f * rs, k2 = rs * rs;
;                 u32x4 w;
; #pragma unroll
;                 for (int n = 0; n < 2; ++n) {
;                     const f32x4 gv = acc[ai][0][m][n], uv = acc[ai][1][m][n];
;                     const unsigned lo = silu_pk((f32x2){gv[0], gv[1]}, (f32x2){uv[0], uv[1]}, k1, k2), hi = silu_pk((f32x2){gv[2], gv[3]}, (f32x2){uv[2], uv[3]}, k1, k2);
;                     if (n == 0) { w.x = lo; w.y = hi; } else { w.z = lo; w.w = hi; }
;                 }
;                 *(u32x4*)(O + (size_t)row * ldc + col0) = w;
	v_pk_fma_f32 v[196:197], v[196:197], v[174:175], v[174:175] op_sel:[0,1,1] op_sel_hi:[1,1,1]
	v_pk_fma_f32 v[198:199], v[198:199], v[174:175], v[174:175] op_sel:[0,1,1] op_sel_hi:[1,1,1]
	v_pk_fma_f32 v[200:201], v[200:201], v[174:175], v[174:175] op_sel:[0,1,1] op_sel_hi:[1,1,1]
	v_pk_fma_f32 v[202:203], v[202:203], v[174:175], v[174:175] op_sel:[0,1,1] op_sel_hi:[1,1,1]
	v_rcp_f32_e32 v188, v188
	v_rcp_f32_e32 v189, v189
	v_rcp_f32_e32 v190, v190
	v_rcp_f32_e32 v191, v191
	v_rcp_f32_e32 v192, v192
	v_rcp_f32_e32 v193, v193
	v_rcp_f32_e32 v194, v194
	v_rcp_f32_e32 v195, v195
	v_rcp_f32_e32 v196, v196
	v_rcp_f32_e32 v197, v197
	v_rcp_f32_e32 v198, v198
	v_rcp_f32_e32 v199, v199
	v_rcp_f32_e32 v200, v200
	v_rcp_f32_e32 v201, v201
	v_rcp_f32_e32 v202, v202
	v_rcp_f32_e32 v203, v203
	v_pk_mul_f32 v[188:189], v[124:125], v[188:189]
	v_pk_mul_f32 v[190:191], v[126:127], v[190:191]
	v_pk_mul_f32 v[192:193], v[112:113], v[192:193]
	v_pk_mul_f32 v[194:195], v[114:115], v[194:195]
	v_pk_mul_f32 v[196:197], v[104:105], v[196:197]
	v_pk_mul_f32 v[198:199], v[106:107], v[198:199]
	v_pk_mul_f32 v[200:201], v[96:97], v[200:201]
	v_pk_mul_f32 v[202:203], v[98:99], v[202:203]
	v_cvt_pk_bf16_f32 v204, v188, v189
	v_cvt_pk_bf16_f32 v205, v190, v191
	v_cvt_pk_bf16_f32 v206, v192, v193
	v_cvt_pk_bf16_f32 v207, v194, v195
	v_cvt_pk_bf16_f32 v208, v196, v197
	v_cvt_pk_bf16_f32 v209, v198, v199
	v_cvt_pk_bf16_f32 v210, v200, v201
	v_cvt_pk_bf16_f32 v211, v202, v203
	ds_bpermute_b32 v226, v153, v204
	ds_bpermute_b32 v227, v153, v205
	ds_bpermute_b32 v228, v153, v206
	ds_bpermute_b32 v229, v153, v207
	ds_bpermute_b32 v230, v153, v208
	ds_bpermute_b32 v231, v153, v209
	ds_bpermute_b32 v232, v153, v210
	ds_bpermute_b32 v233, v153, v211
	v_pk_mul_f32 v[188:189], v[92:93], v[176:177] op_sel_hi:[1,0]
	v_pk_mul_f32 v[190:191], v[94:95], v[176:177] op_sel_hi:[1,0]
	v_pk_mul_f32 v[192:193], v[84:85], v[176:177] op_sel_hi:[1,0]
	v_pk_mul_f32 v[194:195], v[86:87], v[176:177] op_sel_hi:[1,0]
	v_pk_mul_f32 v[196:197], v[76:77], v[178:179] op_sel_hi:[1,0]
	v_pk_mul_f32 v[198:199], v[78:79], v[178:179] op_sel_hi:[1,0]
	v_pk_mul_f32 v[200:201], v[68:69], v[178:179] op_sel_hi:[1,0]
	v_pk_mul_f32 v[202:203], v[70:71], v[178:179] op_sel_hi:[1,0]
	v_exp_f32_e32 v188, v188
	v_exp_f32_e32 v189, v189
	v_exp_f32_e32 v190, v190
	v_exp_f32_e32 v191, v191
	v_exp_f32_e32 v192, v192
	v_exp_f32_e32 v193, v193
	v_exp_f32_e32 v194, v194
	v_exp_f32_e32 v195, v195
	v_exp_f32_e32 v196, v196
	v_exp_f32_e32 v197, v197
	v_exp_f32_e32 v198, v198
	v_exp_f32_e32 v199, v199
	v_exp_f32_e32 v200, v200
	v_exp_f32_e32 v201, v201
	v_exp_f32_e32 v202, v202
	v_exp_f32_e32 v203, v203
	v_pk_fma_f32 v[188:189], v[188:189], v[176:177], v[176:177] op_sel:[0,1,1] op_sel_hi:[1,1,1]
	v_pk_fma_f32 v[190:191], v[190:191], v[176:177], v[176:177] op_sel:[0,1,1] op_sel_hi:[1,1,1]
	v_pk_fma_f32 v[192:193], v[192:193], v[176:177], v[176:177] op_sel:[0,1,1] op_sel_hi:[1,1,1]
	v_pk_fma_f32 v[194:195], v[194:195], v[176:177], v[176:177] op_sel:[0,1,1] op_sel_hi:[1,1,1]
	v_pk_fma_f32 v[196:197], v[196:197], v[178:179], v[178:179] op_sel:[0,1,1] op_sel_hi:[1,1,1]
	v_pk_fma_f32 v[198:199], v[198:199], v[178:179], v[178:179] op_sel:[0,1,1] op_sel_hi:[1,1,1]
	v_pk_fma_f32 v[200:201], v[200:201], v[178:179], v[178:179] op_sel:[0,1,1] op_sel_hi:[1,1,1]
	v_pk_fma_f32 v[202:203], v[202:203], v[178:179], v[178:179] op_sel:[0,1,1] op_sel_hi:[1,1,1]
	v_rcp_f32_e32 v188, v188
	v_rcp_f32_e32 v189, v189
	v_rcp_f32_e32 v190, v190
	v_rcp_f32_e32 v191, v191
	v_rcp_f32_e32 v192, v192
	v_rcp_f32_e32 v193, v193
	v_rcp_f32_e32 v194, v194
	v_rcp_f32_e32 v195, v195
	v_rcp_f32_e32 v196, v196
	v_rcp_f32_e32 v197, v197
	v_rcp_f32_e32 v198, v198
	v_rcp_f32_e32 v199, v199
	v_rcp_f32_e32 v200, v200
	v_rcp_f32_e32 v201, v201
	v_rcp_f32_e32 v202, v202
	v_rcp_f32_e32 v203, v203
	v_pk_mul_f32 v[188:189], v[88:89], v[188:189]
	v_pk_mul_f32 v[190:191], v[90:91], v[190:191]
	v_pk_mul_f32 v[192:193], v[80:81], v[192:193]
	v_pk_mul_f32 v[194:195], v[82:83], v[194:195]
	v_pk_mul_f32 v[196:197], v[72:73], v[196:197]
	v_pk_mul_f32 v[198:199], v[74:75], v[198:199]
	v_pk_mul_f32 v[200:201], v[64:65], v[200:201]
	v_pk_mul_f32 v[202:203], v[66:67], v[202:203]
	v_cvt_pk_bf16_f32 v212, v188, v189
	v_cvt_pk_bf16_f32 v213, v190, v191
	v_cvt_pk_bf16_f32 v214, v192, v193
	v_cvt_pk_bf16_f32 v215, v194, v195
	v_cvt_pk_bf16_f32 v216, v196, v197
	v_cvt_pk_bf16_f32 v217, v198, v199
	v_cvt_pk_bf16_f32 v218, v200, v201
	v_cvt_pk_bf16_f32 v219, v202, v203
	ds_bpermute_b32 v234, v153, v212
	ds_bpermute_b32 v235, v153, v213
	ds_bpermute_b32 v236, v153, v214
	ds_bpermute_b32 v237, v153, v215
	ds_bpermute_b32 v238, v153, v216
	ds_bpermute_b32 v239, v153, v217
	ds_bpermute_b32 v240, v153, v218
	ds_bpermute_b32 v241, v153, v219
	s_waitcnt lgkmcnt(8)
; __device__ __forceinline__ unsigned cvt_pk_bf16(float lo, float hi) { unsigned r; asm volatile("v_cvt_pk_bf16_f32 %0, %1, %2" : "=v"(r) : "v"(lo), "v"(hi)); return r; }
; __device__ __forceinline__ unsigned silu_pk(f32x2 g, f32x2 u, float k1, float k2) {
;     const f32x2 t = g * k1; f32x2 ex; ex.x = __builtin_amdgcn_exp2f(t.x); ex.y = __builtin_amdgcn_exp2f(t.y);
;     const f32x2 d = ex + 1.0f; f32x2 r; r.x = __builtin_amdgcn_rcpf(d.x); r.y = __builtin_amdgcn_rcpf(d.y);
;     const f32x2 o = (g * u) * (r * k2);
;     return cvt_pk_bf16(o.x, o.y);
;     __device__ __forceinline__ void operator()(const f32x4 (&acc)[2][2][4][2], const Unit& u, int wr, int wc, int fr, int fq) const {
;     ...
;             for (int m = 0; m < 4; ++m) {
;                 const int row = row0 + ai * HALF + m * 16; const float rs = __builtin_amdgcn_rsqf(ssq[ai][m] * (1.0f / 1024.0f) + 1e-6f);
;                 const float k1 = -1.4426950408889634f * rs, k2 = rs * rs;
;                 u32x4 w;
; #pragma unroll
;                 for (int n = 0; n < 2; ++n) {
;                     const f32x4 gv = acc[ai][0][m][n], uv = acc[ai][1][m][n];
;                     const unsigned lo = silu_pk((f32x2){gv[0], gv[1]}, (f32x2){uv[0], uv[1]}, k1, k2), hi = silu_pk((f32x2){gv[2], gv[3]}, (f32x2){uv[2], uv[3]}, k1, k2);
;                     if (n == 0) { w.x = lo; w.y = hi; } else { w.z = lo; w.w = hi; }
;                 }
;                 *(u32x4*)(O + (size_t)row * ldc + col0) = w;
	global_store_dwordx4 v[220:221], v[226:229], off
	v_lshl_add_u64 v[220:221], v[220:221], 0, s[96:97]
	global_store_dwordx4 v[220:221], v[230:233], off
	v_lshl_add_u64 v[220:221], v[220:221], 0, s[96:97]
	v_pk_mul_f32 v[188:189], v[60:61], v[180:181] op_sel_hi:[1,0]
	v_pk_mul_f32 v[190:191], v[62:63], v[180:181] op_sel_hi:[1,0]
	v_pk_mul_f32 v[192:193], v[52:53], v[180:181] op_sel_hi:[1,0]
	v_pk_mul_f32 v[194:195], v[54:55], v[180:181] op_sel_hi:[1,0]
	v_pk_mul_f32 v[196:197], v[44:45], v[182:183] op_sel_hi:[1,0]
	v_pk_mul_f32 v[198:199], v[46:47], v[182:183] op_sel_hi:[1,0]
	v_pk_mul_f32 v[200:201], v[36:37], v[182:183] op_sel_hi:[1,0]
	v_pk_mul_f32 v[202:203], v[38:39], v[182:183] op_sel_hi:[1,0]
	v_exp_f32_e32 v188, v188
	v_exp_f32_e32 v189, v189
	v_exp_f32_e32 v190, v190
	v_exp_f32_e32 v191, v191
	v_exp_f32_e32 v192, v192
	v_exp_f32_e32 v193, v193
	v_exp_f32_e32 v194, v194
	v_exp_f32_e32 v195, v195
	v_exp_f32_e32 v196, v196
	v_exp_f32_e32 v197, v197
	v_exp_f32_e32 v198, v198
	v_exp_f32_e32 v199, v199
	v_exp_f32_e32 v200, v200
	v_exp_f32_e32 v201, v201
	v_exp_f32_e32 v202, v202
	v_exp_f32_e32 v203, v203
	v_pk_fma_f32 v[188:189], v[188:189], v[180:181], v[180:181] op_sel:[0,1,1] op_sel_hi:[1,1,1]
	v_pk_fma_f32 v[190:191], v[190:191], v[180:181], v[180:181] op_sel:[0,1,1] op_sel_hi:[1,1,1]
	v_pk_fma_f32 v[192:193], v[192:193], v[180:181], v[180:181] op_sel:[0,1,1] op_sel_hi:[1,1,1]
	v_pk_fma_f32 v[194:195], v[194:195], v[180:181], v[180:181] op_sel:[0,1,1] op_sel_hi:[1,1,1]
	v_pk_fma_f32 v[196:197], v[196:197], v[182:183], v[182:183] op_sel:[0,1,1] op_sel_hi:[1,1,1]
	v_pk_fma_f32 v[198:199], v[198:199], v[182:183], v[182:183] op_sel:[0,1,1] op_sel_hi:[1,1,1]
	v_pk_fma_f32 v[200:201], v[200:201], v[182:183], v[182:183] op_sel:[0,1,1] op_sel_hi:[1,1,1]
	v_pk_fma_f32 v[202:203], v[202:203], v[182:183], v[182:183] op_sel:[0,1,1] op_sel_hi:[1,1,1]
	v_rcp_f32_e32 v188, v188
	v_rcp_f32_e32 v189, v189
	v_rcp_f32_e32 v190, v190
	v_rcp_f32_e32 v191, v191
	v_rcp_f32_e32 v192, v192
	v_rcp_f32_e32 v193, v193
	v_rcp_f32_e32 v194, v194
	v_rcp_f32_e32 v195, v195
	v_rcp_f32_e32 v196, v196
	v_rcp_f32_e32 v197, v197
	v_rcp_f32_e32 v198, v198
	v_rcp_f32_e32 v199, v199
	v_rcp_f32_e32 v200, v200
	v_rcp_f32_e32 v201, v201
	v_rcp_f32_e32 v202, v202
	v_rcp_f32_e32 v203, v203
	v_pk_mul_f32 v[188:189], v[56:57], v[188:189]
	v_pk_mul_f32 v[190:191], v[58:59], v[190:191]
	v_pk_mul_f32 v[192:193], v[48:49], v[192:193]
	v_pk_mul_f32 v[194:195], v[50:51], v[194:195]
	v_pk_mul_f32 v[196:197], v[40:41], v[196:197]
	v_pk_mul_f32 v[198:199], v[42:43], v[198:199]
	v_pk_mul_f32 v[200:201], v[32:33], v[200:201]
	v_pk_mul_f32 v[202:203], v[34:35], v[202:203]
	v_cvt_pk_bf16_f32 v204, v188, v189
	v_cvt_pk_bf16_f32 v205, v190, v191
	v_cvt_pk_bf16_f32 v206, v192, v193
	v_cvt_pk_bf16_f32 v207, v194, v195
	v_cvt_pk_bf16_f32 v208, v196, v197
	v_cvt_pk_bf16_f32 v209, v198, v199
	v_cvt_pk_bf16_f32 v210, v200, v201
	v_cvt_pk_bf16_f32 v211, v202, v203
	ds_bpermute_b32 v226, v153, v204
	ds_bpermute_b32 v227, v153, v205
	ds_bpermute_b32 v228, v153, v206
	ds_bpermute_b32 v229, v153, v207
	ds_bpermute_b32 v230, v153, v208
	ds_bpermute_b32 v231, v153, v209
	ds_bpermute_b32 v232, v153, v210
	ds_bpermute_b32 v233, v153, v211
	s_waitcnt lgkmcnt(8)
	global_store_dwordx4 v[220:221], v[234:237], off
	v_lshl_add_u64 v[220:221], v[220:221], 0, s[96:97]
	global_store_dwordx4 v[220:221], v[238:241], off
	v_lshl_add_u64 v[220:221], v[220:221], 0, s[98:99]
	v_pk_mul_f32 v[188:189], v[28:29], v[184:185] op_sel_hi:[1,0]
	v_pk_mul_f32 v[190:191], v[30:31], v[184:185] op_sel_hi:[1,0]
	v_pk_mul_f32 v[192:193], v[20:21], v[184:185] op_sel_hi:[1,0]
	v_pk_mul_f32 v[194:195], v[22:23], v[184:185] op_sel_hi:[1,0]
	v_pk_mul_f32 v[196:197], v[12:13], v[186:187] op_sel_hi:[1,0]
	v_pk_mul_f32 v[198:199], v[14:15], v[186:187] op_sel_hi:[1,0]
	v_pk_mul_f32 v[200:201], v[4:5], v[186:187] op_sel_hi:[1,0]
	v_pk_mul_f32 v[202:203], v[6:7], v[186:187] op_sel_hi:[1,0]
	v_exp_f32_e32 v188, v188
	v_exp_f32_e32 v189, v189
	v_exp_f32_e32 v190, v190
	v_exp_f32_e32 v191, v191
	v_exp_f32_e32 v192, v192
	v_exp_f32_e32 v193, v193
	v_exp_f32_e32 v194, v194
	v_exp_f32_e32 v195, v195
	v_exp_f32_e32 v196, v196
	v_exp_f32_e32 v197, v197
	v_exp_f32_e32 v198, v198
	v_exp_f32_e32 v199, v199
	v_exp_f32_e32 v200, v200
	v_exp_f32_e32 v201, v201
	v_exp_f32_e32 v202, v202
	v_exp_f32_e32 v203, v203
	v_pk_fma_f32 v[188:189], v[188:189], v[184:185], v[184:185] op_sel:[0,1,1] op_sel_hi:[1,1,1]
	v_pk_fma_f32 v[190:191], v[190:191], v[184:185], v[184:185] op_sel:[0,1,1] op_sel_hi:[1,1,1]
	v_pk_fma_f32 v[192:193], v[192:193], v[184:185], v[184:185] op_sel:[0,1,1] op_sel_hi:[1,1,1]
	v_pk_fma_f32 v[194:195], v[194:195], v[184:185], v[184:185] op_sel:[0,1,1] op_sel_hi:[1,1,1]
	v_pk_fma_f32 v[196:197], v[196:197], v[186:187], v[186:187] op_sel:[0,1,1] op_sel_hi:[1,1,1]
	v_pk_fma_f32 v[198:199], v[198:199], v[186:187], v[186:187] op_sel:[0,1,1] op_sel_hi:[1,1,1]
	v_pk_fma_f32 v[200:201], v[200:201], v[186:187], v[186:187] op_sel:[0,1,1] op_sel_hi:[1,1,1]
	v_pk_fma_f32 v[202:203], v[202:203], v[186:187], v[186:187] op_sel:[0,1,1] op_sel_hi:[1,1,1]
	v_rcp_f32_e32 v188, v188
	v_rcp_f32_e32 v189, v189
	v_rcp_f32_e32 v190, v190
	v_rcp_f32_e32 v191, v191
	v_rcp_f32_e32 v192, v192
	v_rcp_f32_e32 v193, v193
	v_rcp_f32_e32 v194, v194
	v_rcp_f32_e32 v195, v195
	v_rcp_f32_e32 v196, v196
	v_rcp_f32_e32 v197, v197
	v_rcp_f32_e32 v198, v198
	v_rcp_f32_e32 v199, v199
	v_rcp_f32_e32 v200, v200
	v_rcp_f32_e32 v201, v201
	v_rcp_f32_e32 v202, v202
	v_rcp_f32_e32 v203, v203
	v_pk_mul_f32 v[188:189], v[24:25], v[188:189]
	v_pk_mul_f32 v[190:191], v[26:27], v[190:191]
	v_pk_mul_f32 v[192:193], v[16:17], v[192:193]
	v_pk_mul_f32 v[194:195], v[18:19], v[194:195]
	v_pk_mul_f32 v[196:197], v[8:9], v[196:197]
	v_pk_mul_f32 v[198:199], v[10:11], v[198:199]
	v_pk_mul_f32 v[200:201], v[0:1], v[200:201]
	v_pk_mul_f32 v[202:203], v[2:3], v[202:203]
	v_cvt_pk_bf16_f32 v212, v188, v189
	v_cvt_pk_bf16_f32 v213, v190, v191
	v_cvt_pk_bf16_f32 v214, v192, v193
	v_cvt_pk_bf16_f32 v215, v194, v195
	v_cvt_pk_bf16_f32 v216, v196, v197
	v_cvt_pk_bf16_f32 v217, v198, v199
	v_cvt_pk_bf16_f32 v218, v200, v201
	v_cvt_pk_bf16_f32 v219, v202, v203
	ds_bpermute_b32 v234, v153, v212
	ds_bpermute_b32 v235, v153, v213
	ds_bpermute_b32 v236, v153, v214
	ds_bpermute_b32 v237, v153, v215
	ds_bpermute_b32 v238, v153, v216
	ds_bpermute_b32 v239, v153, v217
	ds_bpermute_b32 v240, v153, v218
	ds_bpermute_b32 v241, v153, v219
	s_waitcnt lgkmcnt(8)
	global_store_dwordx4 v[220:221], v[226:229], off
	v_lshl_add_u64 v[220:221], v[220:221], 0, s[96:97]
	global_store_dwordx4 v[220:221], v[230:233], off
	v_lshl_add_u64 v[220:221], v[220:221], 0, s[96:97]
	s_waitcnt lgkmcnt(0)
	global_store_dwordx4 v[220:221], v[234:237], off
	v_lshl_add_u64 v[220:221], v[220:221], 0, s[96:97]
	global_store_dwordx4 v[220:221], v[238:241], off
	s_andn2_b64 vcc, exec, s[4:5]
	s_mov_b64 s[4:5], -1
	s_cbranch_vccnz .LBB0_1190
	s_andn2_b64 vcc, exec, s[6:7]
	s_cbranch_vccnz .LBB0_1189
	s_barrier
	s_branch .LBB0_1189
